# stack4 + GEMM mainloop heads reduced to add/cmp/branch (7 loops)
# baseline (speedup 1.0000x reference)
; template <bool SW>
; __device__ __forceinline__ void gemm_mainloop(const bf16_t* __restrict__ A, int lda, const bf16_t* __restrict__ Bt, int ldb, int K,
;                                               f32x16 (&acc)[2][2], char* lds, int kstart) {
;     ...
;     const bool more = (kt + 1 < nk);
;     if (more) {
;       char* d = ldst + ((kt + 1) & 1) * GEMM_BUF;
;       const int ko = ((kt + 1 + kstart) & (nk - 1)) * 64;
; #pragma unroll
;       for (int i = 0; i < 4; ++i) { glds16(ap[i] + ko, d + i * 1024); glds16(bp[i] + ko, d + 16384 + i * 1024); }
;     }
.LBB0_176:
	s_add_i32 s35, s34, 0x8000
	s_cmp_lt_u32 s3, 15
	s_cbranch_scc0 .LBB0_175
	s_and_b32 s0, s35, 0x8000
	v_readfirstlane_b32 s1, v147
	s_and_b32 s76, s2, 0x3c0
	s_lshl_b32 s76, s76, 1
	s_add_i32 s0, s0, s1
	s_mov_b32 m0, s0
	v_lshl_add_u64 v[138:139], v[116:117], 0, s[76:77]
	global_load_lds_dwordx4 v[138:139], off
	s_add_i32 m0, s0, 0x4000
	v_lshl_add_u64 v[138:139], v[130:131], 0, s[76:77]
	global_load_lds_dwordx4 v[138:139], off
	s_add_i32 m0, s0, 0x400
	v_lshl_add_u64 v[138:139], v[118:119], 0, s[76:77]
	global_load_lds_dwordx4 v[138:139], off
	s_add_i32 m0, s0, 0x4400
	v_lshl_add_u64 v[138:139], v[132:133], 0, s[76:77]
	global_load_lds_dwordx4 v[138:139], off
	s_add_i32 m0, s0, 0x800
	v_lshl_add_u64 v[138:139], v[120:121], 0, s[76:77]
	global_load_lds_dwordx4 v[138:139], off
	s_add_i32 m0, s0, 0x4800
	v_lshl_add_u64 v[138:139], v[134:135], 0, s[76:77]
	global_load_lds_dwordx4 v[138:139], off
	s_add_i32 m0, s0, 0xc00
	v_lshl_add_u64 v[138:139], v[122:123], 0, s[76:77]
	global_load_lds_dwordx4 v[138:139], off
	s_add_i32 m0, s0, 0x4c00
	v_lshl_add_u64 v[138:139], v[136:137], 0, s[76:77]
	global_load_lds_dwordx4 v[138:139], off
	s_branch .LBB0_175

; template <bool SW>
; __device__ __forceinline__ void gemm_mainloop(const bf16_t* __restrict__ A, int lda, const bf16_t* __restrict__ Bt, int ldb, int K,
;                                               f32x16 (&acc)[2][2], char* lds, int kstart) {
;     ...
;     const bool more = (kt + 1 < nk);
;     if (more) {
;       char* d = ldst + ((kt + 1) & 1) * GEMM_BUF;
;       const int ko = ((kt + 1 + kstart) & (nk - 1)) * 64;
; #pragma unroll
;       for (int i = 0; i < 4; ++i) { glds16(ap[i] + ko, d + i * 1024); glds16(bp[i] + ko, d + 16384 + i * 1024); }
;     }
.LBB0_264:
	s_add_i32 s35, s34, 0x8000
	s_cmp_lt_u32 s3, 15
	s_cbranch_scc0 .LBB0_263
	s_and_b32 s0, s35, 0x8000
	v_readfirstlane_b32 s1, v147
	s_and_b32 s76, s2, 0x3c0
	s_lshl_b32 s76, s76, 1
	s_add_i32 s0, s0, s1
	s_mov_b32 m0, s0
	v_lshl_add_u64 v[124:125], v[116:117], 0, s[76:77]
	global_load_lds_dwordx4 v[124:125], off
	s_add_i32 m0, s0, 0x4000
	v_lshl_add_u64 v[124:125], v[130:131], 0, s[76:77]
	global_load_lds_dwordx4 v[124:125], off
	s_add_i32 m0, s0, 0x400
	v_lshl_add_u64 v[124:125], v[118:119], 0, s[76:77]
	global_load_lds_dwordx4 v[124:125], off
	s_add_i32 m0, s0, 0x4400
	v_lshl_add_u64 v[124:125], v[132:133], 0, s[76:77]
	global_load_lds_dwordx4 v[124:125], off
	s_add_i32 m0, s0, 0x800
	v_lshl_add_u64 v[124:125], v[120:121], 0, s[76:77]
	global_load_lds_dwordx4 v[124:125], off
	s_add_i32 m0, s0, 0x4800
	v_lshl_add_u64 v[124:125], v[134:135], 0, s[76:77]
	global_load_lds_dwordx4 v[124:125], off
	s_add_i32 m0, s0, 0xc00
	v_lshl_add_u64 v[124:125], v[122:123], 0, s[76:77]
	global_load_lds_dwordx4 v[124:125], off
	s_add_i32 m0, s0, 0x4c00
	v_lshl_add_u64 v[124:125], v[136:137], 0, s[76:77]
	global_load_lds_dwordx4 v[124:125], off
	s_branch .LBB0_263

; template <bool SW>
; __device__ __forceinline__ void gemm_mainloop(const bf16_t* __restrict__ A, int lda, const bf16_t* __restrict__ Bt, int ldb, int K,
;                                               f32x16 (&acc)[2][2], char* lds, int kstart) {
;     ...
;     const bool more = (kt + 1 < nk);
;     if (more) {
;       char* d = ldst + ((kt + 1) & 1) * GEMM_BUF;
;       const int ko = ((kt + 1 + kstart) & (nk - 1)) * 64;
; #pragma unroll
;       for (int i = 0; i < 4; ++i) { glds16(ap[i] + ko, d + i * 1024); glds16(bp[i] + ko, d + 16384 + i * 1024); }
;     }
.LBB0_563:
	s_add_i32 s44, s43, 0x8000
	s_cmp_lt_u32 s3, 3
	s_cbranch_scc0 .LBB0_562
	s_and_b32 s0, s44, 0x8000
	v_readfirstlane_b32 s1, v114
	s_and_b32 s10, s2, 0xc0
	s_lshl_b32 s10, s10, 1
	s_add_i32 s0, s0, s1
	s_mov_b32 m0, s0
	v_lshl_add_u64 v[108:109], v[92:93], 0, s[10:11]
	global_load_lds_dwordx4 v[108:109], off
	s_add_i32 m0, s0, 0x4000
	v_lshl_add_u64 v[108:109], v[94:95], 0, s[10:11]
	global_load_lds_dwordx4 v[108:109], off
	s_add_i32 m0, s0, 0x400
	v_lshl_add_u64 v[108:109], v[96:97], 0, s[10:11]
	global_load_lds_dwordx4 v[108:109], off
	s_add_i32 m0, s0, 0x4400
	v_lshl_add_u64 v[108:109], v[98:99], 0, s[10:11]
	global_load_lds_dwordx4 v[108:109], off
	s_add_i32 m0, s0, 0x800
	v_lshl_add_u64 v[108:109], v[100:101], 0, s[10:11]
	global_load_lds_dwordx4 v[108:109], off
	s_add_i32 m0, s0, 0x4800
	v_lshl_add_u64 v[108:109], v[102:103], 0, s[10:11]
	global_load_lds_dwordx4 v[108:109], off
	s_add_i32 m0, s0, 0xc00
	v_lshl_add_u64 v[108:109], v[104:105], 0, s[10:11]
	global_load_lds_dwordx4 v[108:109], off
	s_add_i32 m0, s0, 0x4c00
	v_lshl_add_u64 v[108:109], v[106:107], 0, s[10:11]
	global_load_lds_dwordx4 v[108:109], off
	s_branch .LBB0_562

; template <bool SW>
; __device__ __forceinline__ void gemm_mainloop(const bf16_t* __restrict__ A, int lda, const bf16_t* __restrict__ Bt, int ldb, int K,
;                                               f32x16 (&acc)[2][2], char* lds, int kstart) {
;     ...
;     const bool more = (kt + 1 < nk);
;     if (more) {
;       char* d = ldst + ((kt + 1) & 1) * GEMM_BUF;
;       const int ko = ((kt + 1 + kstart) & (nk - 1)) * 64;
; #pragma unroll
;       for (int i = 0; i < 4; ++i) { glds16(ap[i] + ko, d + i * 1024); glds16(bp[i] + ko, d + 16384 + i * 1024); }
;     }
.LBB0_790:
	s_add_i32 s48, s47, 0x8000
	s_cmp_lt_u32 s46, 15
	s_cbranch_scc0 .LBB0_789
	s_and_b32 s0, s48, 0x8000
	v_readfirstlane_b32 s1, v102
	s_and_b32 s10, s45, 0x3c0
	s_lshl_b32 s10, s10, 1
	s_add_i32 s0, s0, s1
	s_mov_b32 m0, s0
	v_lshl_add_u64 v[100:101], v[84:85], 0, s[10:11]
	global_load_lds_dwordx4 v[100:101], off
	s_add_i32 m0, s0, 0x4000
	v_lshl_add_u64 v[100:101], v[86:87], 0, s[10:11]
	global_load_lds_dwordx4 v[100:101], off
	s_add_i32 m0, s0, 0x400
	v_lshl_add_u64 v[100:101], v[88:89], 0, s[10:11]
	global_load_lds_dwordx4 v[100:101], off
	s_add_i32 m0, s0, 0x4400
	v_lshl_add_u64 v[100:101], v[90:91], 0, s[10:11]
	global_load_lds_dwordx4 v[100:101], off
	s_add_i32 m0, s0, 0x800
	v_lshl_add_u64 v[100:101], v[92:93], 0, s[10:11]
	global_load_lds_dwordx4 v[100:101], off
	s_add_i32 m0, s0, 0x4800
	v_lshl_add_u64 v[100:101], v[94:95], 0, s[10:11]
	global_load_lds_dwordx4 v[100:101], off
	s_add_i32 m0, s0, 0xc00
	v_lshl_add_u64 v[100:101], v[96:97], 0, s[10:11]
	global_load_lds_dwordx4 v[100:101], off
	s_add_i32 m0, s0, 0x4c00
	v_lshl_add_u64 v[100:101], v[98:99], 0, s[10:11]
	global_load_lds_dwordx4 v[100:101], off
	s_branch .LBB0_789

; template <bool SW>
; __device__ __forceinline__ void gemm_mainloop(const bf16_t* __restrict__ A, int lda, const bf16_t* __restrict__ Bt, int ldb, int K,
;                                               f32x16 (&acc)[2][2], char* lds, int kstart) {
;     ...
;     const bool more = (kt + 1 < nk);
;     if (more) {
;       char* d = ldst + ((kt + 1) & 1) * GEMM_BUF;
;       const int ko = ((kt + 1 + kstart) & (nk - 1)) * 64;
; #pragma unroll
;       for (int i = 0; i < 4; ++i) { glds16(ap[i] + ko, d + i * 1024); glds16(bp[i] + ko, d + 16384 + i * 1024); }
;     }
.LBB0_796:
	s_add_i32 s40, s39, 0x8000
	s_cmp_lt_u32 s38, 15
	s_cbranch_scc0 .LBB0_795
	s_and_b32 s0, s40, 0x8000
	v_readfirstlane_b32 s1, v102
	s_and_b32 s10, s42, 0x3c0
	s_lshl_b32 s10, s10, 1
	s_add_i32 s0, s0, s1
	s_mov_b32 m0, s0
	v_lshl_add_u64 v[118:119], v[86:87], 0, s[10:11]
	global_load_lds_dwordx4 v[118:119], off
	s_add_i32 m0, s0, 0x4000
	v_lshl_add_u64 v[118:119], v[88:89], 0, s[10:11]
	global_load_lds_dwordx4 v[118:119], off
	s_add_i32 m0, s0, 0x400
	v_lshl_add_u64 v[118:119], v[90:91], 0, s[10:11]
	global_load_lds_dwordx4 v[118:119], off
	s_add_i32 m0, s0, 0x4400
	v_lshl_add_u64 v[118:119], v[92:93], 0, s[10:11]
	global_load_lds_dwordx4 v[118:119], off
	s_add_i32 m0, s0, 0x800
	v_lshl_add_u64 v[118:119], v[94:95], 0, s[10:11]
	global_load_lds_dwordx4 v[118:119], off
	s_add_i32 m0, s0, 0x4800
	v_lshl_add_u64 v[118:119], v[96:97], 0, s[10:11]
	global_load_lds_dwordx4 v[118:119], off
	s_add_i32 m0, s0, 0xc00
	v_lshl_add_u64 v[118:119], v[98:99], 0, s[10:11]
	global_load_lds_dwordx4 v[118:119], off
	s_add_i32 m0, s0, 0x4c00
	v_lshl_add_u64 v[118:119], v[100:101], 0, s[10:11]
	global_load_lds_dwordx4 v[118:119], off
	s_branch .LBB0_795

; template <bool SW>
; __device__ __forceinline__ void gemm_mainloop(const bf16_t* __restrict__ A, int lda, const bf16_t* __restrict__ Bt, int ldb, int K,
;                                               f32x16 (&acc)[2][2], char* lds, int kstart) {
;     ...
;     const bool more = (kt + 1 < nk);
;     if (more) {
;       char* d = ldst + ((kt + 1) & 1) * GEMM_BUF;
;       const int ko = ((kt + 1 + kstart) & (nk - 1)) * 64;
; #pragma unroll
;       for (int i = 0; i < 4; ++i) { glds16(ap[i] + ko, d + i * 1024); glds16(bp[i] + ko, d + 16384 + i * 1024); }
;     }
.LBB0_872:
	s_add_i32 s42, s41, 0x8000
	s_cmp_lt_u32 s40, 15
	s_cbranch_scc0 .LBB0_871
	s_and_b32 s0, s42, 0x8000
	v_readfirstlane_b32 s1, v97
	s_and_b32 s12, s39, 0x3c0
	s_lshl_b32 s12, s12, 1
	s_add_i32 s0, s0, s1
	s_mov_b32 m0, s0
	v_lshl_add_u64 v[112:113], v[80:81], 0, s[12:13]
	global_load_lds_dwordx4 v[112:113], off
	s_add_i32 m0, s0, 0x4000
	v_lshl_add_u64 v[112:113], v[82:83], 0, s[12:13]
	global_load_lds_dwordx4 v[112:113], off
	s_add_i32 m0, s0, 0x400
	v_lshl_add_u64 v[112:113], v[84:85], 0, s[12:13]
	global_load_lds_dwordx4 v[112:113], off
	s_add_i32 m0, s0, 0x4400
	v_lshl_add_u64 v[112:113], v[86:87], 0, s[12:13]
	global_load_lds_dwordx4 v[112:113], off
	s_add_i32 m0, s0, 0x800
	v_lshl_add_u64 v[112:113], v[88:89], 0, s[12:13]
	global_load_lds_dwordx4 v[112:113], off
	s_add_i32 m0, s0, 0x4800
	v_lshl_add_u64 v[112:113], v[90:91], 0, s[12:13]
	global_load_lds_dwordx4 v[112:113], off
	s_add_i32 m0, s0, 0xc00
	v_lshl_add_u64 v[112:113], v[92:93], 0, s[12:13]
	global_load_lds_dwordx4 v[112:113], off
	s_add_i32 m0, s0, 0x4c00
	v_lshl_add_u64 v[112:113], v[94:95], 0, s[12:13]
	global_load_lds_dwordx4 v[112:113], off
	s_branch .LBB0_871

; template <bool SW>
; __device__ __forceinline__ void gemm_mainloop(const bf16_t* __restrict__ A, int lda, const bf16_t* __restrict__ Bt, int ldb, int K,
;                                               f32x16 (&acc)[2][2], char* lds, int kstart) {
;     ...
;     const bool more = (kt + 1 < nk);
;     if (more) {
;       char* d = ldst + ((kt + 1) & 1) * GEMM_BUF;
;       const int ko = ((kt + 1 + kstart) & (nk - 1)) * 64;
; #pragma unroll
;       for (int i = 0; i < 4; ++i) { glds16(ap[i] + ko, d + i * 1024); glds16(bp[i] + ko, d + 16384 + i * 1024); }
;     }
.LBB0_1021:
	s_add_i32 s41, s40, 0x8000
	s_cmp_lt_u32 s39, 15
	s_cbranch_scc0 .LBB0_1020
	s_and_b32 s0, s41, 0x8000
	v_readfirstlane_b32 s1, v99
	s_and_b32 s14, s38, 0x3c0
	s_lshl_b32 s14, s14, 1
	s_add_i32 s0, s0, s1
	s_mov_b32 m0, s0
	v_lshl_add_u64 v[114:115], v[82:83], 0, s[14:15]
	global_load_lds_dwordx4 v[114:115], off
	s_add_i32 m0, s0, 0x4000
	v_lshl_add_u64 v[114:115], v[84:85], 0, s[14:15]
	global_load_lds_dwordx4 v[114:115], off
	s_add_i32 m0, s0, 0x400
	v_lshl_add_u64 v[114:115], v[86:87], 0, s[14:15]
	global_load_lds_dwordx4 v[114:115], off
	s_add_i32 m0, s0, 0x4400
	v_lshl_add_u64 v[114:115], v[88:89], 0, s[14:15]
	global_load_lds_dwordx4 v[114:115], off
	s_add_i32 m0, s0, 0x800
	v_lshl_add_u64 v[114:115], v[90:91], 0, s[14:15]
	global_load_lds_dwordx4 v[114:115], off
	s_add_i32 m0, s0, 0x4800
	v_lshl_add_u64 v[114:115], v[92:93], 0, s[14:15]
	global_load_lds_dwordx4 v[114:115], off
	s_add_i32 m0, s0, 0xc00
	v_lshl_add_u64 v[114:115], v[94:95], 0, s[14:15]
	global_load_lds_dwordx4 v[114:115], off
	s_add_i32 m0, s0, 0x4c00
	v_lshl_add_u64 v[114:115], v[96:97], 0, s[14:15]
	global_load_lds_dwordx4 v[114:115], off
	s_branch .LBB0_1020
